# P1/P11 SwiGLU epilogue: the 8 row-scale loads hoisted before the unit's K-loop into dead VGPRs (epilogue picks them up with v_mov)
# baseline (speedup 1.0000x reference)
;     __device__ __forceinline__ void operator()(const f32x4 (&acc)[2][2][4][2], const Unit& u, int wr, int wc, int fr, int fq) const {
;         const int row0 = u.pm * BM + wr * 64 + fr, col0 = u.pn * HALF + wc * 32 + 8 * fq;
;         float rvv[2][4];
; #pragma unroll
;         for (int ai = 0; ai < 2; ++ai)
; #pragma unroll
;             for (int m = 0; m < 4; ++m) rvv[ai][m] = rs[row0 + ai * HALF + m * 16];
; template <class Epi, class Sched, bool ALIGN_EPI = false, bool SP2 = false>
; __device__ __forceinline__ void gemm_phase(PG8_LAS unsigned char* lds, const Gemm g, const Sched& S, const Epi& E) {
;     ...
; #pragma unroll
;         for (int a = 0; a < 2; ++a)
; #pragma unroll
;             for (int b = 0; b < 2; ++b)
; #pragma unroll
;                 for (int m = 0; m < 4; ++m)
; #pragma unroll
;                     for (int n = 0; n < 2; ++n) acc[a][b][m][n] = (f32x4){0.f, 0.f, 0.f, 0.f};
;         cur = nxt; cA = nA; cB = nB; ++ui;
.LBB0_98:
	s_ashr_i32 s15, s14, 31
	s_lshl_b64 s[16:17], s[14:15], 19
	s_add_u32 s16, s92, s16
	s_addc_u32 s17, s93, s17
	s_and_b64 s[18:19], s[2:3], exec
	s_cselect_b32 s15, s17, s23
	s_cselect_b32 s43, s16, s22
	s_ashr_i32 s13, s12, 31
	s_lshl_b64 s[18:19], s[12:13], 19
	s_add_u32 s18, s4, s18
	s_addc_u32 s19, s5, s19
	s_and_b64 s[26:27], s[2:3], exec
	s_cselect_b32 s13, s19, s25
	s_cselect_b32 s44, s18, s24
	s_add_u32 s22, s22, 0x40080
	s_addc_u32 s23, s23, 0
	s_add_u32 s45, s24, 0x100
	v_mov_b32_e32 v2, 0
	s_addc_u32 s46, s25, 0
	s_mov_b32 s47, -2
	v_mov_b32_e32 v3, v2
	v_mov_b32_e32 v4, v2
	v_mov_b32_e32 v5, v2
	v_mov_b32_e32 v6, v2
	v_mov_b32_e32 v7, v2
	v_mov_b32_e32 v8, v2
	v_mov_b32_e32 v9, v2
	v_mov_b32_e32 v18, v2
	v_mov_b32_e32 v19, v2
	v_mov_b32_e32 v20, v2
	v_mov_b32_e32 v21, v2
	v_mov_b32_e32 v22, v2
	v_mov_b32_e32 v23, v2
	v_mov_b32_e32 v24, v2
	v_mov_b32_e32 v25, v2
	v_mov_b32_e32 v34, v2
	v_mov_b32_e32 v35, v2
	v_mov_b32_e32 v36, v2
	v_mov_b32_e32 v37, v2
	v_mov_b32_e32 v38, v2
	v_mov_b32_e32 v39, v2
	v_mov_b32_e32 v40, v2
	v_mov_b32_e32 v41, v2
	v_mov_b32_e32 v50, v2
	v_mov_b32_e32 v51, v2
	v_mov_b32_e32 v52, v2
	v_mov_b32_e32 v53, v2
	v_mov_b32_e32 v54, v2
	v_mov_b32_e32 v55, v2
	v_mov_b32_e32 v56, v2
	v_mov_b32_e32 v57, v2
	v_mov_b32_e32 v10, v2
	v_mov_b32_e32 v11, v2
	v_mov_b32_e32 v12, v2
	v_mov_b32_e32 v13, v2
	v_mov_b32_e32 v14, v2
	v_mov_b32_e32 v15, v2
	v_mov_b32_e32 v16, v2
	v_mov_b32_e32 v17, v2
	v_mov_b32_e32 v26, v2
	v_mov_b32_e32 v27, v2
	v_mov_b32_e32 v28, v2
	v_mov_b32_e32 v29, v2
	v_mov_b32_e32 v30, v2
	v_mov_b32_e32 v31, v2
	v_mov_b32_e32 v32, v2
	v_mov_b32_e32 v33, v2
	v_mov_b32_e32 v42, v2
	v_mov_b32_e32 v43, v2
	v_mov_b32_e32 v44, v2
	v_mov_b32_e32 v45, v2
	v_mov_b32_e32 v46, v2
	v_mov_b32_e32 v47, v2
	v_mov_b32_e32 v48, v2
	v_mov_b32_e32 v49, v2
	v_mov_b32_e32 v58, v2
	v_mov_b32_e32 v59, v2
	v_mov_b32_e32 v60, v2
	v_mov_b32_e32 v61, v2
	v_mov_b32_e32 v62, v2
	v_mov_b32_e32 v63, v2
	v_mov_b32_e32 v64, v2
	v_mov_b32_e32 v65, v2
	v_mov_b32_e32 v66, v2
	v_mov_b32_e32 v67, v2
	v_mov_b32_e32 v68, v2
	v_mov_b32_e32 v69, v2
	v_mov_b32_e32 v70, v2
	v_mov_b32_e32 v71, v2
	v_mov_b32_e32 v72, v2
	v_mov_b32_e32 v73, v2
	v_mov_b32_e32 v82, v2
	v_mov_b32_e32 v83, v2
	v_mov_b32_e32 v84, v2
	v_mov_b32_e32 v85, v2
	v_mov_b32_e32 v86, v2
	v_mov_b32_e32 v87, v2
	v_mov_b32_e32 v88, v2
	v_mov_b32_e32 v89, v2
	v_mov_b32_e32 v98, v2
	v_mov_b32_e32 v99, v2
	v_mov_b32_e32 v100, v2
	v_mov_b32_e32 v101, v2
	v_mov_b32_e32 v102, v2
	v_mov_b32_e32 v103, v2
	v_mov_b32_e32 v104, v2
	v_mov_b32_e32 v105, v2
	v_mov_b32_e32 v122, v2
	v_mov_b32_e32 v123, v2
	v_mov_b32_e32 v124, v2
	v_mov_b32_e32 v125, v2
	v_mov_b32_e32 v126, v2
	v_mov_b32_e32 v127, v2
	v_mov_b32_e32 v128, v2
	v_mov_b32_e32 v129, v2
	v_mov_b32_e32 v74, v2
	v_mov_b32_e32 v75, v2
	v_mov_b32_e32 v76, v2
	v_mov_b32_e32 v77, v2
	v_mov_b32_e32 v78, v2
	v_mov_b32_e32 v79, v2
	v_mov_b32_e32 v80, v2
	v_mov_b32_e32 v81, v2
	v_mov_b32_e32 v90, v2
	v_mov_b32_e32 v91, v2
	v_mov_b32_e32 v92, v2
	v_mov_b32_e32 v93, v2
	v_mov_b32_e32 v94, v2
	v_mov_b32_e32 v95, v2
	v_mov_b32_e32 v96, v2
	v_mov_b32_e32 v97, v2
	v_mov_b32_e32 v106, v2
	v_mov_b32_e32 v107, v2
	v_mov_b32_e32 v108, v2
	v_mov_b32_e32 v109, v2
	v_mov_b32_e32 v110, v2
	v_mov_b32_e32 v111, v2
	v_mov_b32_e32 v112, v2
	v_mov_b32_e32 v113, v2
	v_mov_b32_e32 v114, v2
	v_mov_b32_e32 v115, v2
	v_mov_b32_e32 v116, v2
	v_mov_b32_e32 v117, v2
	v_mov_b32_e32 v118, v2
	v_mov_b32_e32 v119, v2
	v_mov_b32_e32 v120, v2
	v_mov_b32_e32 v121, v2
	v_lshl_add_u32 v236, s20, 8, v148
	v_ashrrev_i32_e32 v237, 31, v236
	v_lshl_add_u64 v[242:243], v[236:237], 2, s[82:83]
	global_load_dword v244, v[242:243], off
	global_load_dword v246, v[242:243], off offset:512
	global_load_dword v247, v[242:243], off offset:576
	global_load_dword v248, v[242:243], off offset:640
	global_load_dword v251, v[242:243], off offset:704
	v_or_b32_e32 v252, 16, v236
	v_ashrrev_i32_e32 v253, 31, v252
	v_lshl_add_u64 v[252:253], v[252:253], 2, s[82:83]
	global_load_dword v245, v[252:253], off
	v_or_b32_e32 v252, 32, v236
	v_ashrrev_i32_e32 v253, 31, v252
	v_lshl_add_u64 v[252:253], v[252:253], 2, s[82:83]
	global_load_dword v249, v[252:253], off
	v_or_b32_e32 v252, 48, v236
	v_ashrrev_i32_e32 v253, 31, v252
	v_lshl_add_u64 v[252:253], v[252:253], 2, s[82:83]
	global_load_dword v250, v[252:253], off

; __device__ __forceinline__ unsigned cvt_pk_bf16(float lo, float hi) { unsigned r; asm volatile("v_cvt_pk_bf16_f32 %0, %1, %2" : "=v"(r) : "v"(lo), "v"(hi)); return r; }
;     __device__ __forceinline__ void operator()(const f32x4 (&acc)[2][2][4][2], const Unit& u, int wr, int wc, int fr, int fq) const {
;         const int row0 = u.pm * BM + wr * 64 + fr, col0 = u.pn * HALF + wc * 32 + 8 * fq;
;         float rvv[2][4];
; #pragma unroll
;         for (int ai = 0; ai < 2; ++ai)
; #pragma unroll
;             for (int m = 0; m < 4; ++m) rvv[ai][m] = rs[row0 + ai * HALF + m * 16];
; #pragma unroll
;         for (int ai = 0; ai < 2; ++ai)
; #pragma unroll
;             for (int m = 0; m < 4; ++m) {
;                 bf16_t* rowp = O + (size_t)(row0 + ai * HALF + m * 16) * ldc + col0;
;                 const float rv = rvv[ai][m], rn = rv * -1.4426950408889634f, r2 = rv * rv;
;                 const f32x4 g0 = acc[ai][0][m][0], g1 = acc[ai][0][m][1], u0 = acc[ai][1][m][0], u1 = acc[ai][1][m][1];
;                 const f32x4 t0 = g0 * rn, t1 = g1 * rn;
;                 f32x4 d0, d1;
; #pragma unroll
;                 for (int k = 0; k < 4; ++k) { d0[k] = __builtin_amdgcn_exp2f(t0[k]); d1[k] = __builtin_amdgcn_exp2f(t1[k]); }
;                 d0 = d0 + 1.0f; d1 = d1 + 1.0f;
; #pragma unroll
;                 for (int k = 0; k < 4; ++k) { d0[k] = __builtin_amdgcn_rcpf(d0[k]); d1[k] = __builtin_amdgcn_rcpf(d1[k]); }
;                 const f32x4 o0 = (g0 * u0) * r2 * d0, o1 = (g1 * u1) * r2 * d1;
;                 u32x4 w;
;                 w.x = cvt_pk_bf16(o0[0], o0[1]); w.y = cvt_pk_bf16(o0[2], o0[3]); w.z = cvt_pk_bf16(o1[0], o1[1]); w.w = cvt_pk_bf16(o1[2], o1[3]);
;                 *(u32x4*)rowp = w;
.LBB0_102:
	v_lshl_add_u32 v154, s20, 8, v148
	v_ashrrev_i32_e32 v155, 31, v154
	v_lshl_add_u64 v[156:157], v[154:155], 2, s[82:83]
	v_mov_b32_e32 v165, v244
	v_or_b32_e32 v158, 16, v154
	v_ashrrev_i32_e32 v159, 31, v158
	v_lshl_add_u64 v[146:147], v[158:159], 2, s[82:83]
	v_mov_b32_e32 v178, v245
	v_lshl_or_b32 v160, s42, 7, v150
	v_pk_mul_f32 v[168:169], v[116:117], v[124:125]
	v_or_b32_e32 v172, 32, v154
	v_or_b32_e32 v124, 48, v154
	v_ashrrev_i32_e32 v161, 31, v160
	v_ashrrev_i32_e32 v173, 31, v172
	v_ashrrev_i32_e32 v125, 31, v124
	v_pk_mul_f32 v[170:171], v[114:115], v[122:123]
	v_lshlrev_b64 v[122:123], 1, v[160:161]
	v_lshl_add_u64 v[160:161], v[172:173], 2, s[82:83]
	v_lshl_add_u64 v[174:175], v[124:125], 2, s[82:83]
	v_mov_b32_e32 v173, v246
	v_mov_b32_e32 v181, v247
	v_mov_b32_e32 v182, v248
	v_mov_b32_e32 v183, v249
	v_mov_b32_e32 v184, v250
	v_mov_b32_e32 v125, v251
	v_pk_mul_f32 v[128:129], v[120:121], v[128:129]
	v_pk_mul_f32 v[166:167], v[118:119], v[126:127]
	v_readlane_b32 s22, v254, 37
	v_readlane_b32 s23, v254, 38
	v_add_u32_e32 v179, 0x80, v154
	v_add_u32_e32 v180, 0x90, v154
	v_mov_b64_e32 v[146:147], s[22:23]
	v_add_u32_e32 v127, 0xa0, v154
	v_add_u32_e32 v126, 0xb0, v154
	v_mad_i64_i32 v[154:155], s[22:23], v154, s41, v[146:147]
	v_lshl_add_u64 v[154:155], v[154:155], 0, v[122:123]
	v_pk_mul_f32 v[100:101], v[108:109], v[100:101]
	v_pk_mul_f32 v[98:99], v[106:107], v[98:99]
	v_pk_mul_f32 v[104:105], v[112:113], v[104:105]
	v_pk_mul_f32 v[102:103], v[110:111], v[102:103]
	v_mad_i64_i32 v[158:159], s[22:23], v158, s41, v[146:147]
	v_lshl_add_u64 v[158:159], v[158:159], 0, v[122:123]
	v_pk_mul_f32 v[84:85], v[92:93], v[84:85]
	v_pk_mul_f32 v[82:83], v[90:91], v[82:83]
	v_pk_mul_f32 v[88:89], v[96:97], v[88:89]
	v_pk_mul_f32 v[86:87], v[94:95], v[86:87]
	v_pk_mul_f32 v[68:69], v[76:77], v[68:69]
	v_pk_mul_f32 v[66:67], v[74:75], v[66:67]
	v_pk_mul_f32 v[72:73], v[80:81], v[72:73]
	v_pk_mul_f32 v[70:71], v[78:79], v[70:71]
	v_pk_mul_f32 v[52:53], v[60:61], v[52:53]
	v_pk_mul_f32 v[50:51], v[58:59], v[50:51]
	v_pk_mul_f32 v[56:57], v[64:65], v[56:57]
	v_pk_mul_f32 v[54:55], v[62:63], v[54:55]
	v_pk_mul_f32 v[36:37], v[44:45], v[36:37]
	v_pk_mul_f32 v[34:35], v[42:43], v[34:35]
	v_pk_mul_f32 v[40:41], v[48:49], v[40:41]
	v_pk_mul_f32 v[38:39], v[46:47], v[38:39]
	v_pk_mul_f32 v[20:21], v[28:29], v[20:21]
	v_pk_mul_f32 v[18:19], v[26:27], v[18:19]
	v_pk_mul_f32 v[24:25], v[32:33], v[24:25]
	v_pk_mul_f32 v[22:23], v[30:31], v[22:23]
	v_pk_mul_f32 v[4:5], v[12:13], v[4:5]
	v_pk_mul_f32 v[2:3], v[10:11], v[2:3]
	v_pk_mul_f32 v[8:9], v[16:17], v[8:9]
	v_pk_mul_f32 v[6:7], v[14:15], v[6:7]
	s_andn2_b64 vcc, exec, s[2:3]
	s_mov_b64 s[2:3], -1
	s_waitcnt vmcnt(0)
	v_mul_f32_e32 v156, 0xbfb8aa3b, v165
	v_pk_mul_f32 v[120:121], v[120:121], v[156:157] op_sel_hi:[1,0]
	v_pk_mul_f32 v[116:117], v[116:117], v[156:157] op_sel_hi:[1,0]
	v_pk_mul_f32 v[114:115], v[114:115], v[156:157] op_sel_hi:[1,0]
	v_pk_mul_f32 v[118:119], v[118:119], v[156:157] op_sel_hi:[1,0]
	v_exp_f32_e32 v114, v114
	v_exp_f32_e32 v115, v115
	v_exp_f32_e32 v120, v120
	v_exp_f32_e32 v116, v116
	v_exp_f32_e32 v121, v121
	v_exp_f32_e32 v117, v117
	v_exp_f32_e32 v118, v118
	v_exp_f32_e32 v119, v119
	v_mul_f32_e32 v160, v165, v165
	v_pk_mul_f32 v[156:157], v[166:167], v[160:161] op_sel_hi:[1,0]
	v_pk_mul_f32 v[128:129], v[128:129], v[160:161] op_sel_hi:[1,0]
	v_pk_mul_f32 v[166:167], v[170:171], v[160:161] op_sel_hi:[1,0]
	v_pk_mul_f32 v[160:161], v[168:169], v[160:161] op_sel_hi:[1,0]
	v_mul_f32_e32 v168, 0xbfb8aa3b, v178
	v_pk_add_f32 v[120:121], v[120:121], 1.0 op_sel_hi:[1,0]
	v_pk_add_f32 v[116:117], v[116:117], 1.0 op_sel_hi:[1,0]
	v_pk_add_f32 v[114:115], v[114:115], 1.0 op_sel_hi:[1,0]
	v_pk_mul_f32 v[170:171], v[112:113], v[168:169] op_sel_hi:[1,0]
	v_pk_mul_f32 v[174:175], v[110:111], v[168:169] op_sel_hi:[1,0]
	v_pk_mul_f32 v[176:177], v[108:109], v[168:169] op_sel_hi:[1,0]
	v_pk_mul_f32 v[168:169], v[106:107], v[168:169] op_sel_hi:[1,0]
	v_pk_add_f32 v[118:119], v[118:119], 1.0 op_sel_hi:[1,0]
	v_rcp_f32_e32 v114, v114
	v_rcp_f32_e32 v115, v115
	v_rcp_f32_e32 v120, v120
	v_rcp_f32_e32 v116, v116
	v_rcp_f32_e32 v121, v121
	v_rcp_f32_e32 v117, v117
	v_exp_f32_e32 v168, v168
	v_exp_f32_e32 v169, v169
	v_exp_f32_e32 v176, v176
	v_exp_f32_e32 v177, v177
	v_rcp_f32_e32 v118, v118
	v_rcp_f32_e32 v119, v119
	v_exp_f32_e32 v174, v174
	v_exp_f32_e32 v175, v175
	v_exp_f32_e32 v170, v170
	v_exp_f32_e32 v171, v171
	v_pk_mul_f32 v[120:121], v[128:129], v[120:121]
	v_pk_mul_f32 v[128:129], v[160:161], v[116:117]
	v_pk_mul_f32 v[116:117], v[166:167], v[114:115]
	v_pk_add_f32 v[176:177], v[176:177], 1.0 op_sel_hi:[1,0]
	v_pk_add_f32 v[168:169], v[168:169], 1.0 op_sel_hi:[1,0]
	v_pk_mul_f32 v[118:119], v[156:157], v[118:119]
	v_pk_add_f32 v[170:171], v[170:171], 1.0 op_sel_hi:[1,0]
	v_cvt_pk_bf16_f32 v114, v118, v119
	v_cvt_pk_bf16_f32 v115, v120, v121
	v_cvt_pk_bf16_f32 v116, v116, v117
	v_cvt_pk_bf16_f32 v117, v128, v129
	v_pk_add_f32 v[174:175], v[174:175], 1.0 op_sel_hi:[1,0]
	v_rcp_f32_e32 v168, v168
	global_store_dwordx4 v[154:155], v[114:117], off
	v_rcp_f32_e32 v169, v169
	v_rcp_f32_e32 v174, v174
	v_rcp_f32_e32 v116, v176
	v_rcp_f32_e32 v117, v177
	v_rcp_f32_e32 v175, v175
	v_rcp_f32_e32 v114, v170
	v_rcp_f32_e32 v115, v171
	v_mul_f32_e32 v118, v178, v178
	v_pk_mul_f32 v[98:99], v[98:99], v[118:119] op_sel_hi:[1,0]
	v_pk_mul_f32 v[100:101], v[100:101], v[118:119] op_sel_hi:[1,0]
	v_pk_mul_f32 v[102:103], v[102:103], v[118:119] op_sel_hi:[1,0]
	v_pk_mul_f32 v[104:105], v[104:105], v[118:119] op_sel_hi:[1,0]
	v_pk_mul_f32 v[106:107], v[100:101], v[116:117]
; __device__ __forceinline__ unsigned cvt_pk_bf16(float lo, float hi) { unsigned r; asm volatile("v_cvt_pk_bf16_f32 %0, %1, %2" : "=v"(r) : "v"(lo), "v"(hi)); return r; }
;     __device__ __forceinline__ void operator()(const f32x4 (&acc)[2][2][4][2], const Unit& u, int wr, int wc, int fr, int fq) const {
;     ...
;         for (int ai = 0; ai < 2; ++ai)
; #pragma unroll
;             for (int m = 0; m < 4; ++m) {
;                 bf16_t* rowp = O + (size_t)(row0 + ai * HALF + m * 16) * ldc + col0;
;                 const float rv = rvv[ai][m], rn = rv * -1.4426950408889634f, r2 = rv * rv;
;                 const f32x4 g0 = acc[ai][0][m][0], g1 = acc[ai][0][m][1], u0 = acc[ai][1][m][0], u1 = acc[ai][1][m][1];
;                 const f32x4 t0 = g0 * rn, t1 = g1 * rn;
;                 f32x4 d0, d1;
; #pragma unroll
;                 for (int k = 0; k < 4; ++k) { d0[k] = __builtin_amdgcn_exp2f(t0[k]); d1[k] = __builtin_amdgcn_exp2f(t1[k]); }
;                 d0 = d0 + 1.0f; d1 = d1 + 1.0f;
; #pragma unroll
;                 for (int k = 0; k < 4; ++k) { d0[k] = __builtin_amdgcn_rcpf(d0[k]); d1[k] = __builtin_amdgcn_rcpf(d1[k]); }
;                 const f32x4 o0 = (g0 * u0) * r2 * d0, o1 = (g1 * u1) * r2 * d1;
;                 u32x4 w;
;                 w.x = cvt_pk_bf16(o0[0], o0[1]); w.y = cvt_pk_bf16(o0[2], o0[3]); w.z = cvt_pk_bf16(o1[0], o1[1]); w.w = cvt_pk_bf16(o1[2], o1[3]);
;                 *(u32x4*)rowp = w;
	v_pk_mul_f32 v[100:101], v[98:99], v[168:169]
	v_pk_mul_f32 v[104:105], v[104:105], v[114:115]
	v_pk_mul_f32 v[102:103], v[102:103], v[174:175]
	v_mul_f32_e32 v108, v183, v183
	v_cvt_pk_bf16_f32 v98, v102, v103
	v_cvt_pk_bf16_f32 v99, v104, v105
	v_cvt_pk_bf16_f32 v100, v100, v101
	v_cvt_pk_bf16_f32 v101, v106, v107
	global_store_dwordx4 v[158:159], v[98:101], off
	v_pk_mul_f32 v[82:83], v[82:83], v[108:109] op_sel_hi:[1,0]
	v_pk_mul_f32 v[84:85], v[84:85], v[108:109] op_sel_hi:[1,0]
	v_mul_f32_e32 v100, 0xbfb8aa3b, v183
	v_pk_mul_f32 v[102:103], v[96:97], v[100:101] op_sel_hi:[1,0]
	v_pk_mul_f32 v[104:105], v[94:95], v[100:101] op_sel_hi:[1,0]
	v_pk_mul_f32 v[106:107], v[92:93], v[100:101] op_sel_hi:[1,0]
	v_pk_mul_f32 v[100:101], v[90:91], v[100:101] op_sel_hi:[1,0]
	v_exp_f32_e32 v106, v106
	v_exp_f32_e32 v100, v100
	v_exp_f32_e32 v101, v101
	v_exp_f32_e32 v107, v107
	v_exp_f32_e32 v104, v104
	v_exp_f32_e32 v105, v105
	v_exp_f32_e32 v102, v102
	v_exp_f32_e32 v103, v103
	v_pk_add_f32 v[106:107], v[106:107], 1.0 op_sel_hi:[1,0]
	v_pk_add_f32 v[100:101], v[100:101], 1.0 op_sel_hi:[1,0]
	v_pk_add_f32 v[104:105], v[104:105], 1.0 op_sel_hi:[1,0]
	v_pk_add_f32 v[102:103], v[102:103], 1.0 op_sel_hi:[1,0]
	v_rcp_f32_e32 v100, v100
	v_rcp_f32_e32 v101, v101
	v_rcp_f32_e32 v106, v106
	v_rcp_f32_e32 v107, v107
	v_rcp_f32_e32 v104, v104
	v_rcp_f32_e32 v105, v105
	v_rcp_f32_e32 v102, v102
	v_rcp_f32_e32 v103, v103
	v_mad_i64_i32 v[98:99], s[22:23], v172, s41, v[146:147]
	v_pk_mul_f32 v[86:87], v[86:87], v[108:109] op_sel_hi:[1,0]
	v_pk_mul_f32 v[88:89], v[88:89], v[108:109] op_sel_hi:[1,0]
	v_pk_mul_f32 v[90:91], v[84:85], v[106:107]
	v_pk_mul_f32 v[84:85], v[82:83], v[100:101]
	v_lshl_add_u64 v[98:99], v[98:99], 0, v[122:123]
	v_pk_mul_f32 v[88:89], v[88:89], v[102:103]
	v_pk_mul_f32 v[86:87], v[86:87], v[104:105]
	v_mul_f32_e32 v92, v184, v184
	v_cvt_pk_bf16_f32 v82, v86, v87
	v_cvt_pk_bf16_f32 v83, v88, v89
	v_cvt_pk_bf16_f32 v84, v84, v85
	v_cvt_pk_bf16_f32 v85, v90, v91
	global_store_dwordx4 v[98:99], v[82:85], off
	v_pk_mul_f32 v[66:67], v[66:67], v[92:93] op_sel_hi:[1,0]
	v_pk_mul_f32 v[68:69], v[68:69], v[92:93] op_sel_hi:[1,0]
	v_mul_f32_e32 v84, 0xbfb8aa3b, v184
	v_pk_mul_f32 v[86:87], v[80:81], v[84:85] op_sel_hi:[1,0]
	v_pk_mul_f32 v[88:89], v[78:79], v[84:85] op_sel_hi:[1,0]
	v_pk_mul_f32 v[90:91], v[76:77], v[84:85] op_sel_hi:[1,0]
	v_pk_mul_f32 v[84:85], v[74:75], v[84:85] op_sel_hi:[1,0]
	v_exp_f32_e32 v90, v90
	v_exp_f32_e32 v84, v84
	v_exp_f32_e32 v85, v85
	v_exp_f32_e32 v91, v91
	v_exp_f32_e32 v88, v88
	v_exp_f32_e32 v89, v89
	v_exp_f32_e32 v86, v86
	v_exp_f32_e32 v87, v87
	v_pk_add_f32 v[90:91], v[90:91], 1.0 op_sel_hi:[1,0]
	v_pk_add_f32 v[84:85], v[84:85], 1.0 op_sel_hi:[1,0]
	v_pk_add_f32 v[88:89], v[88:89], 1.0 op_sel_hi:[1,0]
	v_pk_add_f32 v[86:87], v[86:87], 1.0 op_sel_hi:[1,0]
	v_rcp_f32_e32 v84, v84
	v_rcp_f32_e32 v85, v85
	v_rcp_f32_e32 v90, v90
	v_rcp_f32_e32 v91, v91
	v_rcp_f32_e32 v88, v88
	v_rcp_f32_e32 v89, v89
	v_rcp_f32_e32 v86, v86
	v_rcp_f32_e32 v87, v87
	v_mad_i64_i32 v[82:83], s[22:23], v124, s41, v[146:147]
	v_pk_mul_f32 v[70:71], v[70:71], v[92:93] op_sel_hi:[1,0]
	v_pk_mul_f32 v[72:73], v[72:73], v[92:93] op_sel_hi:[1,0]
	v_pk_mul_f32 v[74:75], v[68:69], v[90:91]
	v_pk_mul_f32 v[68:69], v[66:67], v[84:85]
	v_lshl_add_u64 v[82:83], v[82:83], 0, v[122:123]
	v_pk_mul_f32 v[72:73], v[72:73], v[86:87]
	v_pk_mul_f32 v[70:71], v[70:71], v[88:89]
	v_mul_f32_e32 v76, v173, v173
	v_cvt_pk_bf16_f32 v66, v70, v71
	v_cvt_pk_bf16_f32 v67, v72, v73
	v_cvt_pk_bf16_f32 v68, v68, v69
	v_cvt_pk_bf16_f32 v69, v74, v75
	global_store_dwordx4 v[82:83], v[66:69], off
	v_pk_mul_f32 v[50:51], v[50:51], v[76:77] op_sel_hi:[1,0]
	v_pk_mul_f32 v[52:53], v[52:53], v[76:77] op_sel_hi:[1,0]
	v_mul_f32_e32 v68, 0xbfb8aa3b, v173
	v_pk_mul_f32 v[70:71], v[64:65], v[68:69] op_sel_hi:[1,0]
	v_pk_mul_f32 v[72:73], v[62:63], v[68:69] op_sel_hi:[1,0]
	v_pk_mul_f32 v[74:75], v[60:61], v[68:69] op_sel_hi:[1,0]
	v_pk_mul_f32 v[68:69], v[58:59], v[68:69] op_sel_hi:[1,0]
	v_exp_f32_e32 v74, v74
	v_exp_f32_e32 v68, v68
	v_exp_f32_e32 v69, v69
	v_exp_f32_e32 v75, v75
	v_exp_f32_e32 v72, v72
	v_exp_f32_e32 v73, v73
	v_exp_f32_e32 v70, v70
	v_exp_f32_e32 v71, v71
	v_pk_add_f32 v[74:75], v[74:75], 1.0 op_sel_hi:[1,0]
	v_pk_add_f32 v[68:69], v[68:69], 1.0 op_sel_hi:[1,0]
	v_pk_add_f32 v[72:73], v[72:73], 1.0 op_sel_hi:[1,0]
	v_pk_add_f32 v[70:71], v[70:71], 1.0 op_sel_hi:[1,0]
	v_rcp_f32_e32 v68, v68
	v_rcp_f32_e32 v69, v69
	v_rcp_f32_e32 v74, v74
	v_rcp_f32_e32 v75, v75
	v_rcp_f32_e32 v72, v72
	v_rcp_f32_e32 v73, v73
	v_rcp_f32_e32 v70, v70
	v_rcp_f32_e32 v71, v71
	v_mad_i64_i32 v[66:67], s[22:23], v179, s41, v[146:147]
	v_pk_mul_f32 v[54:55], v[54:55], v[76:77] op_sel_hi:[1,0]
	v_pk_mul_f32 v[56:57], v[56:57], v[76:77] op_sel_hi:[1,0]
	v_pk_mul_f32 v[58:59], v[52:53], v[74:75]
	v_pk_mul_f32 v[52:53], v[50:51], v[68:69]
	v_lshl_add_u64 v[66:67], v[66:67], 0, v[122:123]
	v_pk_mul_f32 v[56:57], v[56:57], v[70:71]
	v_pk_mul_f32 v[54:55], v[54:55], v[72:73]
; __device__ __forceinline__ unsigned cvt_pk_bf16(float lo, float hi) { unsigned r; asm volatile("v_cvt_pk_bf16_f32 %0, %1, %2" : "=v"(r) : "v"(lo), "v"(hi)); return r; }
;     __device__ __forceinline__ void operator()(const f32x4 (&acc)[2][2][4][2], const Unit& u, int wr, int wc, int fr, int fq) const {
;     ...
;         for (int ai = 0; ai < 2; ++ai)
; #pragma unroll
;             for (int m = 0; m < 4; ++m) {
;                 bf16_t* rowp = O + (size_t)(row0 + ai * HALF + m * 16) * ldc + col0;
;                 const float rv = rvv[ai][m], rn = rv * -1.4426950408889634f, r2 = rv * rv;
;                 const f32x4 g0 = acc[ai][0][m][0], g1 = acc[ai][0][m][1], u0 = acc[ai][1][m][0], u1 = acc[ai][1][m][1];
;                 const f32x4 t0 = g0 * rn, t1 = g1 * rn;
;                 f32x4 d0, d1;
; #pragma unroll
;                 for (int k = 0; k < 4; ++k) { d0[k] = __builtin_amdgcn_exp2f(t0[k]); d1[k] = __builtin_amdgcn_exp2f(t1[k]); }
;                 d0 = d0 + 1.0f; d1 = d1 + 1.0f;
; #pragma unroll
;                 for (int k = 0; k < 4; ++k) { d0[k] = __builtin_amdgcn_rcpf(d0[k]); d1[k] = __builtin_amdgcn_rcpf(d1[k]); }
;                 const f32x4 o0 = (g0 * u0) * r2 * d0, o1 = (g1 * u1) * r2 * d1;
;                 u32x4 w;
;                 w.x = cvt_pk_bf16(o0[0], o0[1]); w.y = cvt_pk_bf16(o0[2], o0[3]); w.z = cvt_pk_bf16(o1[0], o1[1]); w.w = cvt_pk_bf16(o1[2], o1[3]);
;                 *(u32x4*)rowp = w;
;             }
	v_mul_f32_e32 v60, v181, v181
	v_cvt_pk_bf16_f32 v50, v54, v55
	v_cvt_pk_bf16_f32 v51, v56, v57
	v_cvt_pk_bf16_f32 v52, v52, v53
	v_cvt_pk_bf16_f32 v53, v58, v59
	global_store_dwordx4 v[66:67], v[50:53], off
	v_pk_mul_f32 v[34:35], v[34:35], v[60:61] op_sel_hi:[1,0]
	v_pk_mul_f32 v[36:37], v[36:37], v[60:61] op_sel_hi:[1,0]
	v_mul_f32_e32 v52, 0xbfb8aa3b, v181
	v_pk_mul_f32 v[54:55], v[48:49], v[52:53] op_sel_hi:[1,0]
	v_pk_mul_f32 v[56:57], v[46:47], v[52:53] op_sel_hi:[1,0]
	v_pk_mul_f32 v[58:59], v[44:45], v[52:53] op_sel_hi:[1,0]
	v_pk_mul_f32 v[52:53], v[42:43], v[52:53] op_sel_hi:[1,0]
	v_exp_f32_e32 v58, v58
	v_exp_f32_e32 v52, v52
	v_exp_f32_e32 v53, v53
	v_exp_f32_e32 v59, v59
	v_exp_f32_e32 v56, v56
	v_exp_f32_e32 v57, v57
	v_exp_f32_e32 v54, v54
	v_exp_f32_e32 v55, v55
	v_pk_add_f32 v[58:59], v[58:59], 1.0 op_sel_hi:[1,0]
	v_pk_add_f32 v[52:53], v[52:53], 1.0 op_sel_hi:[1,0]
	v_pk_add_f32 v[56:57], v[56:57], 1.0 op_sel_hi:[1,0]
	v_pk_add_f32 v[54:55], v[54:55], 1.0 op_sel_hi:[1,0]
	v_rcp_f32_e32 v52, v52
	v_rcp_f32_e32 v53, v53
	v_rcp_f32_e32 v58, v58
	v_rcp_f32_e32 v59, v59
	v_rcp_f32_e32 v56, v56
	v_rcp_f32_e32 v57, v57
	v_rcp_f32_e32 v54, v54
	v_rcp_f32_e32 v55, v55
	v_mad_i64_i32 v[50:51], s[22:23], v180, s41, v[146:147]
	v_pk_mul_f32 v[38:39], v[38:39], v[60:61] op_sel_hi:[1,0]
	v_pk_mul_f32 v[40:41], v[40:41], v[60:61] op_sel_hi:[1,0]
	v_pk_mul_f32 v[42:43], v[36:37], v[58:59]
	v_pk_mul_f32 v[36:37], v[34:35], v[52:53]
	v_lshl_add_u64 v[50:51], v[50:51], 0, v[122:123]
	v_pk_mul_f32 v[40:41], v[40:41], v[54:55]
	v_pk_mul_f32 v[38:39], v[38:39], v[56:57]
	v_mul_f32_e32 v44, v182, v182
	v_cvt_pk_bf16_f32 v34, v38, v39
	v_cvt_pk_bf16_f32 v35, v40, v41
	v_cvt_pk_bf16_f32 v36, v36, v37
	v_cvt_pk_bf16_f32 v37, v42, v43
	global_store_dwordx4 v[50:51], v[34:37], off
	v_pk_mul_f32 v[18:19], v[18:19], v[44:45] op_sel_hi:[1,0]
	v_pk_mul_f32 v[20:21], v[20:21], v[44:45] op_sel_hi:[1,0]
	v_mul_f32_e32 v36, 0xbfb8aa3b, v182
	v_pk_mul_f32 v[38:39], v[32:33], v[36:37] op_sel_hi:[1,0]
	v_pk_mul_f32 v[40:41], v[30:31], v[36:37] op_sel_hi:[1,0]
	v_pk_mul_f32 v[42:43], v[28:29], v[36:37] op_sel_hi:[1,0]
	v_pk_mul_f32 v[36:37], v[26:27], v[36:37] op_sel_hi:[1,0]
	v_exp_f32_e32 v42, v42
	v_exp_f32_e32 v36, v36
	v_exp_f32_e32 v37, v37
	v_exp_f32_e32 v43, v43
	v_exp_f32_e32 v40, v40
	v_exp_f32_e32 v41, v41
	v_exp_f32_e32 v38, v38
	v_exp_f32_e32 v39, v39
	v_pk_add_f32 v[42:43], v[42:43], 1.0 op_sel_hi:[1,0]
	v_pk_add_f32 v[36:37], v[36:37], 1.0 op_sel_hi:[1,0]
	v_pk_add_f32 v[40:41], v[40:41], 1.0 op_sel_hi:[1,0]
	v_pk_add_f32 v[38:39], v[38:39], 1.0 op_sel_hi:[1,0]
	v_rcp_f32_e32 v36, v36
	v_rcp_f32_e32 v37, v37
	v_rcp_f32_e32 v42, v42
	v_rcp_f32_e32 v43, v43
	v_rcp_f32_e32 v40, v40
	v_rcp_f32_e32 v41, v41
	v_rcp_f32_e32 v38, v38
	v_rcp_f32_e32 v39, v39
	v_mad_i64_i32 v[34:35], s[22:23], v127, s41, v[146:147]
	v_pk_mul_f32 v[22:23], v[22:23], v[44:45] op_sel_hi:[1,0]
	v_pk_mul_f32 v[24:25], v[24:25], v[44:45] op_sel_hi:[1,0]
	v_pk_mul_f32 v[26:27], v[20:21], v[42:43]
	v_pk_mul_f32 v[20:21], v[18:19], v[36:37]
	v_lshl_add_u64 v[34:35], v[34:35], 0, v[122:123]
	v_pk_mul_f32 v[24:25], v[24:25], v[38:39]
	v_pk_mul_f32 v[22:23], v[22:23], v[40:41]
	v_mul_f32_e32 v28, v125, v125
	v_cvt_pk_bf16_f32 v18, v22, v23
	v_cvt_pk_bf16_f32 v19, v24, v25
	v_cvt_pk_bf16_f32 v20, v20, v21
	v_cvt_pk_bf16_f32 v21, v26, v27
	global_store_dwordx4 v[34:35], v[18:21], off
	v_pk_mul_f32 v[2:3], v[2:3], v[28:29] op_sel_hi:[1,0]
	v_pk_mul_f32 v[4:5], v[4:5], v[28:29] op_sel_hi:[1,0]
	v_mul_f32_e32 v20, 0xbfb8aa3b, v125
	v_pk_mul_f32 v[22:23], v[16:17], v[20:21] op_sel_hi:[1,0]
	v_pk_mul_f32 v[24:25], v[14:15], v[20:21] op_sel_hi:[1,0]
	v_pk_mul_f32 v[26:27], v[12:13], v[20:21] op_sel_hi:[1,0]
	v_pk_mul_f32 v[20:21], v[10:11], v[20:21] op_sel_hi:[1,0]
	v_exp_f32_e32 v26, v26
	v_exp_f32_e32 v20, v20
	v_exp_f32_e32 v21, v21
	v_exp_f32_e32 v27, v27
	v_exp_f32_e32 v24, v24
	v_exp_f32_e32 v25, v25
	v_exp_f32_e32 v22, v22
	v_exp_f32_e32 v23, v23
	v_pk_add_f32 v[26:27], v[26:27], 1.0 op_sel_hi:[1,0]
	v_pk_add_f32 v[20:21], v[20:21], 1.0 op_sel_hi:[1,0]
	v_pk_add_f32 v[24:25], v[24:25], 1.0 op_sel_hi:[1,0]
	v_pk_add_f32 v[22:23], v[22:23], 1.0 op_sel_hi:[1,0]
	v_rcp_f32_e32 v20, v20
	v_rcp_f32_e32 v21, v21
	v_rcp_f32_e32 v26, v26
	v_rcp_f32_e32 v27, v27
	v_rcp_f32_e32 v24, v24
	v_rcp_f32_e32 v25, v25
	v_rcp_f32_e32 v22, v22
	v_rcp_f32_e32 v23, v23
	v_mad_i64_i32 v[18:19], s[22:23], v126, s41, v[146:147]
	v_lshl_add_u64 v[18:19], v[18:19], 0, v[122:123]
	v_pk_mul_f32 v[6:7], v[6:7], v[28:29] op_sel_hi:[1,0]
	v_pk_mul_f32 v[8:9], v[8:9], v[28:29] op_sel_hi:[1,0]
	v_pk_mul_f32 v[10:11], v[4:5], v[26:27]
	v_pk_mul_f32 v[4:5], v[2:3], v[20:21]
	v_pk_mul_f32 v[8:9], v[8:9], v[22:23]
	v_pk_mul_f32 v[6:7], v[6:7], v[24:25]
	s_nop 0
	v_cvt_pk_bf16_f32 v2, v6, v7
	v_cvt_pk_bf16_f32 v3, v8, v9
	v_cvt_pk_bf16_f32 v4, v4, v5
	v_cvt_pk_bf16_f32 v5, v10, v11
	global_store_dwordx4 v[18:19], v[2:5], off
	s_cbranch_vccnz .LBB0_91
	s_andn2_b64 vcc, exec, s[0:1]
	s_cbranch_vccnz .LBB0_90
	s_barrier
	s_branch .LBB0_90

;     __device__ __forceinline__ void operator()(const f32x4 (&acc)[2][2][4][2], const Unit& u, int wr, int wc, int fr, int fq) const {
;         const int row0 = u.pm * BM + wr * 64 + fr, col0 = u.pn * HALF + wc * 32 + 8 * fq;
;         float rvv[2][4];
; #pragma unroll
;         for (int ai = 0; ai < 2; ++ai)
; #pragma unroll
;             for (int m = 0; m < 4; ++m) rvv[ai][m] = rs[row0 + ai * HALF + m * 16];
; template <class Epi, class Sched, bool ALIGN_EPI = false, bool SP2 = false>
; __device__ __forceinline__ void gemm_phase(PG8_LAS unsigned char* lds, const Gemm g, const Sched& S, const Epi& E) {
;     ...
; #pragma unroll
;         for (int a = 0; a < 2; ++a)
; #pragma unroll
;             for (int b = 0; b < 2; ++b)
; #pragma unroll
;                 for (int m = 0; m < 4; ++m)
; #pragma unroll
;                     for (int n = 0; n < 2; ++n) acc[a][b][m][n] = (f32x4){0.f, 0.f, 0.f, 0.f};
;         cur = nxt; cA = nA; cB = nB; ++ui;
.LBB0_1562:
	s_ashr_i32 s13, s12, 31
	s_lshl_b64 s[14:15], s[12:13], 19
	v_readlane_b32 s16, v254, 59
	v_readlane_b32 s17, v254, 60
	s_add_u32 s14, s16, s14
	s_addc_u32 s15, s17, s15
	s_and_b64 s[16:17], s[6:7], exec
	s_cselect_b32 s13, s15, s21
	s_cselect_b32 s41, s14, s20
	s_ashr_i32 s11, s10, 31
	s_lshl_b64 s[16:17], s[10:11], 19
	v_readlane_b32 s24, v254, 46
	v_readlane_b32 s25, v254, 47
	s_add_u32 s16, s24, s16
	s_addc_u32 s17, s25, s17
	s_and_b64 s[24:25], s[6:7], exec
	s_cselect_b32 s11, s17, s23
	s_cselect_b32 s42, s16, s22
	s_add_u32 s20, s20, 0x40080
	s_addc_u32 s21, s21, 0
	s_add_u32 s43, s22, 0x100
	v_mov_b32_e32 v2, 0
	s_addc_u32 s44, s23, 0
	s_mov_b32 s45, -2
	v_mov_b32_e32 v3, v2
	v_mov_b32_e32 v4, v2
	v_mov_b32_e32 v5, v2
	v_mov_b32_e32 v6, v2
	v_mov_b32_e32 v7, v2
	v_mov_b32_e32 v8, v2
	v_mov_b32_e32 v9, v2
	s_waitcnt vmcnt(0)
	v_mov_b32_e32 v18, v2
	v_mov_b32_e32 v19, v2
	v_mov_b32_e32 v20, v2
	v_mov_b32_e32 v21, v2
	v_mov_b32_e32 v22, v2
	v_mov_b32_e32 v23, v2
	v_mov_b32_e32 v24, v2
	v_mov_b32_e32 v25, v2
	v_mov_b32_e32 v34, v2
	v_mov_b32_e32 v35, v2
	v_mov_b32_e32 v36, v2
	v_mov_b32_e32 v37, v2
	v_mov_b32_e32 v38, v2
	v_mov_b32_e32 v39, v2
	v_mov_b32_e32 v40, v2
	v_mov_b32_e32 v41, v2
	v_mov_b32_e32 v50, v2
	v_mov_b32_e32 v51, v2
	v_mov_b32_e32 v52, v2
	v_mov_b32_e32 v53, v2
	v_mov_b32_e32 v54, v2
	v_mov_b32_e32 v55, v2
	v_mov_b32_e32 v56, v2
	v_mov_b32_e32 v57, v2
	v_mov_b32_e32 v10, v2
	v_mov_b32_e32 v11, v2
	v_mov_b32_e32 v12, v2
	v_mov_b32_e32 v13, v2
	v_mov_b32_e32 v14, v2
	v_mov_b32_e32 v15, v2
	v_mov_b32_e32 v16, v2
	v_mov_b32_e32 v17, v2
	v_mov_b32_e32 v26, v2
	v_mov_b32_e32 v27, v2
	v_mov_b32_e32 v28, v2
	v_mov_b32_e32 v29, v2
	v_mov_b32_e32 v30, v2
	v_mov_b32_e32 v31, v2
	v_mov_b32_e32 v32, v2
	v_mov_b32_e32 v33, v2
	v_mov_b32_e32 v42, v2
	v_mov_b32_e32 v43, v2
	v_mov_b32_e32 v44, v2
	v_mov_b32_e32 v45, v2
	v_mov_b32_e32 v46, v2
	v_mov_b32_e32 v47, v2
	v_mov_b32_e32 v48, v2
	v_mov_b32_e32 v49, v2
	v_mov_b32_e32 v58, v2
	v_mov_b32_e32 v59, v2
	v_mov_b32_e32 v60, v2
	v_mov_b32_e32 v61, v2
	v_mov_b32_e32 v62, v2
	v_mov_b32_e32 v63, v2
	v_mov_b32_e32 v64, v2
	v_mov_b32_e32 v65, v2
	v_mov_b32_e32 v66, v2
	v_mov_b32_e32 v67, v2
	v_mov_b32_e32 v68, v2
	v_mov_b32_e32 v69, v2
	v_mov_b32_e32 v70, v2
	v_mov_b32_e32 v71, v2
	v_mov_b32_e32 v72, v2
	v_mov_b32_e32 v73, v2
	v_mov_b32_e32 v82, v2
	v_mov_b32_e32 v83, v2
	v_mov_b32_e32 v84, v2
	v_mov_b32_e32 v85, v2
	v_mov_b32_e32 v86, v2
	v_mov_b32_e32 v87, v2
	v_mov_b32_e32 v88, v2
	v_mov_b32_e32 v89, v2
	v_mov_b32_e32 v98, v2
	v_mov_b32_e32 v99, v2
	v_mov_b32_e32 v100, v2
	v_mov_b32_e32 v101, v2
	v_mov_b32_e32 v102, v2
	v_mov_b32_e32 v103, v2
	v_mov_b32_e32 v104, v2
	v_mov_b32_e32 v105, v2
	v_mov_b32_e32 v122, v2
	v_mov_b32_e32 v123, v2
	v_mov_b32_e32 v124, v2
	v_mov_b32_e32 v125, v2
	v_mov_b32_e32 v126, v2
	v_mov_b32_e32 v127, v2
	v_mov_b32_e32 v128, v2
	v_mov_b32_e32 v129, v2
	v_mov_b32_e32 v74, v2
	v_mov_b32_e32 v75, v2
	v_mov_b32_e32 v76, v2
	v_mov_b32_e32 v77, v2
	v_mov_b32_e32 v78, v2
	v_mov_b32_e32 v79, v2
	v_mov_b32_e32 v80, v2
	v_mov_b32_e32 v81, v2
	v_mov_b32_e32 v90, v2
	v_mov_b32_e32 v91, v2
	v_mov_b32_e32 v92, v2
	v_mov_b32_e32 v93, v2
	v_mov_b32_e32 v94, v2
	v_mov_b32_e32 v95, v2
	v_mov_b32_e32 v96, v2
	v_mov_b32_e32 v97, v2
	v_mov_b32_e32 v106, v2
	v_mov_b32_e32 v107, v2
	v_mov_b32_e32 v108, v2
	v_mov_b32_e32 v109, v2
	v_mov_b32_e32 v110, v2
	v_mov_b32_e32 v111, v2
	v_mov_b32_e32 v112, v2
	v_mov_b32_e32 v113, v2
	v_mov_b32_e32 v114, v2
	v_mov_b32_e32 v115, v2
	v_mov_b32_e32 v116, v2
	v_mov_b32_e32 v117, v2
	v_mov_b32_e32 v118, v2
	v_mov_b32_e32 v119, v2
	v_mov_b32_e32 v120, v2
	v_mov_b32_e32 v121, v2
	v_lshl_add_u32 v236, s18, 8, v1
	v_ashrrev_i32_e32 v237, 31, v236
	v_lshl_add_u64 v[242:243], v[236:237], 2, s[82:83]
	global_load_dword v244, v[242:243], off
	global_load_dword v246, v[242:243], off offset:512
	global_load_dword v247, v[242:243], off offset:576
	global_load_dword v248, v[242:243], off offset:640
	global_load_dword v251, v[242:243], off offset:704
	v_or_b32_e32 v252, 16, v236
	v_ashrrev_i32_e32 v253, 31, v252
	v_lshl_add_u64 v[252:253], v[252:253], 2, s[82:83]
	global_load_dword v245, v[252:253], off
	v_or_b32_e32 v252, 32, v236
	v_ashrrev_i32_e32 v253, 31, v252
	v_lshl_add_u64 v[252:253], v[252:253], 2, s[82:83]
	global_load_dword v249, v[252:253], off
	v_or_b32_e32 v252, 48, v236
	v_ashrrev_i32_e32 v253, 31, v252
	v_lshl_add_u64 v[252:253], v[252:253], 2, s[82:83]
	global_load_dword v250, v[252:253], off

; __device__ __forceinline__ unsigned cvt_pk_bf16(float lo, float hi) { unsigned r; asm volatile("v_cvt_pk_bf16_f32 %0, %1, %2" : "=v"(r) : "v"(lo), "v"(hi)); return r; }
;     __device__ __forceinline__ void operator()(const f32x4 (&acc)[2][2][4][2], const Unit& u, int wr, int wc, int fr, int fq) const {
;         const int row0 = u.pm * BM + wr * 64 + fr, col0 = u.pn * HALF + wc * 32 + 8 * fq;
;         float rvv[2][4];
; #pragma unroll
;         for (int ai = 0; ai < 2; ++ai)
; #pragma unroll
;             for (int m = 0; m < 4; ++m) rvv[ai][m] = rs[row0 + ai * HALF + m * 16];
; #pragma unroll
;         for (int ai = 0; ai < 2; ++ai)
; #pragma unroll
;             for (int m = 0; m < 4; ++m) {
;                 bf16_t* rowp = O + (size_t)(row0 + ai * HALF + m * 16) * ldc + col0;
;                 const float rv = rvv[ai][m], rn = rv * -1.4426950408889634f, r2 = rv * rv;
;                 const f32x4 g0 = acc[ai][0][m][0], g1 = acc[ai][0][m][1], u0 = acc[ai][1][m][0], u1 = acc[ai][1][m][1];
;                 const f32x4 t0 = g0 * rn, t1 = g1 * rn;
;                 f32x4 d0, d1;
; #pragma unroll
;                 for (int k = 0; k < 4; ++k) { d0[k] = __builtin_amdgcn_exp2f(t0[k]); d1[k] = __builtin_amdgcn_exp2f(t1[k]); }
;                 d0 = d0 + 1.0f; d1 = d1 + 1.0f;
; #pragma unroll
;                 for (int k = 0; k < 4; ++k) { d0[k] = __builtin_amdgcn_rcpf(d0[k]); d1[k] = __builtin_amdgcn_rcpf(d1[k]); }
;                 const f32x4 o0 = (g0 * u0) * r2 * d0, o1 = (g1 * u1) * r2 * d1;
;                 u32x4 w;
;                 w.x = cvt_pk_bf16(o0[0], o0[1]); w.y = cvt_pk_bf16(o0[2], o0[3]); w.z = cvt_pk_bf16(o1[0], o1[1]); w.w = cvt_pk_bf16(o1[2], o1[3]);
;                 *(u32x4*)rowp = w;
.LBB0_1566:
	v_lshl_add_u32 v156, s18, 8, v1
	v_ashrrev_i32_e32 v157, 31, v156
	v_lshl_add_u64 v[158:159], v[156:157], 2, s[82:83]
	v_mov_b32_e32 v155, v244
	v_or_b32_e32 v160, 16, v156
	v_ashrrev_i32_e32 v161, 31, v160
	v_lshl_add_u64 v[148:149], v[160:161], 2, s[82:83]
	v_mov_b32_e32 v165, v245
	v_lshl_or_b32 v168, s40, 7, v151
	v_pk_mul_f32 v[172:173], v[116:117], v[124:125]
	v_or_b32_e32 v176, 32, v156
	v_or_b32_e32 v124, 48, v156
	v_ashrrev_i32_e32 v169, 31, v168
	v_ashrrev_i32_e32 v177, 31, v176
	v_ashrrev_i32_e32 v125, 31, v124
	v_pk_mul_f32 v[174:175], v[114:115], v[122:123]
	v_lshlrev_b64 v[122:123], 1, v[168:169]
	v_lshl_add_u64 v[168:169], v[176:177], 2, s[82:83]
	v_lshl_add_u64 v[178:179], v[124:125], 2, s[82:83]
	v_mov_b32_e32 v177, v246
	v_mov_b32_e32 v184, v247
	v_mov_b32_e32 v185, v248
	v_mov_b32_e32 v191, v249
	v_mov_b32_e32 v192, v250
	v_mov_b32_e32 v125, v251
	v_pk_mul_f32 v[128:129], v[120:121], v[128:129]
	v_pk_mul_f32 v[170:171], v[118:119], v[126:127]
	v_readlane_b32 s20, v254, 37
	v_readlane_b32 s21, v254, 38
	v_add_u32_e32 v182, 0x80, v156
	v_add_u32_e32 v183, 0x90, v156
	v_mov_b64_e32 v[148:149], s[20:21]
	v_add_u32_e32 v127, 0xa0, v156
	v_add_u32_e32 v126, 0xb0, v156
	v_mad_i64_i32 v[156:157], s[20:21], v156, s39, v[148:149]
	v_lshl_add_u64 v[156:157], v[156:157], 0, v[122:123]
	v_pk_mul_f32 v[100:101], v[108:109], v[100:101]
	v_pk_mul_f32 v[98:99], v[106:107], v[98:99]
	v_pk_mul_f32 v[104:105], v[112:113], v[104:105]
	v_pk_mul_f32 v[102:103], v[110:111], v[102:103]
	v_mad_i64_i32 v[160:161], s[20:21], v160, s39, v[148:149]
	v_lshl_add_u64 v[160:161], v[160:161], 0, v[122:123]
	v_pk_mul_f32 v[84:85], v[92:93], v[84:85]
	v_pk_mul_f32 v[82:83], v[90:91], v[82:83]
	v_pk_mul_f32 v[88:89], v[96:97], v[88:89]
	v_pk_mul_f32 v[86:87], v[94:95], v[86:87]
	v_pk_mul_f32 v[68:69], v[76:77], v[68:69]
	v_pk_mul_f32 v[66:67], v[74:75], v[66:67]
	v_pk_mul_f32 v[72:73], v[80:81], v[72:73]
	v_pk_mul_f32 v[70:71], v[78:79], v[70:71]
	v_pk_mul_f32 v[52:53], v[60:61], v[52:53]
	v_pk_mul_f32 v[50:51], v[58:59], v[50:51]
	v_pk_mul_f32 v[56:57], v[64:65], v[56:57]
	v_pk_mul_f32 v[54:55], v[62:63], v[54:55]
	v_pk_mul_f32 v[36:37], v[44:45], v[36:37]
	v_pk_mul_f32 v[34:35], v[42:43], v[34:35]
	v_pk_mul_f32 v[40:41], v[48:49], v[40:41]
	v_pk_mul_f32 v[38:39], v[46:47], v[38:39]
	v_pk_mul_f32 v[20:21], v[28:29], v[20:21]
	v_pk_mul_f32 v[18:19], v[26:27], v[18:19]
	v_pk_mul_f32 v[24:25], v[32:33], v[24:25]
	v_pk_mul_f32 v[22:23], v[30:31], v[22:23]
	v_pk_mul_f32 v[4:5], v[12:13], v[4:5]
	v_pk_mul_f32 v[2:3], v[10:11], v[2:3]
	v_pk_mul_f32 v[8:9], v[16:17], v[8:9]
	v_pk_mul_f32 v[6:7], v[14:15], v[6:7]
	s_andn2_b64 vcc, exec, s[6:7]
	s_mov_b64 s[6:7], -1
	s_waitcnt vmcnt(0)
	v_mul_f32_e32 v158, 0xbfb8aa3b, v155
	v_pk_mul_f32 v[120:121], v[120:121], v[158:159] op_sel_hi:[1,0]
	v_pk_mul_f32 v[116:117], v[116:117], v[158:159] op_sel_hi:[1,0]
	v_pk_mul_f32 v[114:115], v[114:115], v[158:159] op_sel_hi:[1,0]
	v_pk_mul_f32 v[118:119], v[118:119], v[158:159] op_sel_hi:[1,0]
	v_exp_f32_e32 v114, v114
	v_exp_f32_e32 v115, v115
	v_exp_f32_e32 v120, v120
	v_exp_f32_e32 v116, v116
	v_exp_f32_e32 v121, v121
	v_exp_f32_e32 v117, v117
	v_exp_f32_e32 v118, v118
	v_exp_f32_e32 v119, v119
	v_mul_f32_e32 v168, v155, v155
	v_pk_mul_f32 v[158:159], v[170:171], v[168:169] op_sel_hi:[1,0]
	v_pk_mul_f32 v[128:129], v[128:129], v[168:169] op_sel_hi:[1,0]
	v_pk_mul_f32 v[170:171], v[174:175], v[168:169] op_sel_hi:[1,0]
	v_pk_mul_f32 v[168:169], v[172:173], v[168:169] op_sel_hi:[1,0]
	v_mul_f32_e32 v172, 0xbfb8aa3b, v165
	v_pk_add_f32 v[120:121], v[120:121], 1.0 op_sel_hi:[1,0]
	v_pk_add_f32 v[116:117], v[116:117], 1.0 op_sel_hi:[1,0]
	v_pk_add_f32 v[114:115], v[114:115], 1.0 op_sel_hi:[1,0]
	v_pk_mul_f32 v[174:175], v[112:113], v[172:173] op_sel_hi:[1,0]
	v_pk_mul_f32 v[178:179], v[110:111], v[172:173] op_sel_hi:[1,0]
	v_pk_mul_f32 v[180:181], v[108:109], v[172:173] op_sel_hi:[1,0]
	v_pk_mul_f32 v[172:173], v[106:107], v[172:173] op_sel_hi:[1,0]
	v_pk_add_f32 v[118:119], v[118:119], 1.0 op_sel_hi:[1,0]
	v_rcp_f32_e32 v114, v114
	v_rcp_f32_e32 v115, v115
	v_rcp_f32_e32 v120, v120
	v_rcp_f32_e32 v116, v116
	v_rcp_f32_e32 v121, v121
	v_rcp_f32_e32 v117, v117
	v_exp_f32_e32 v172, v172
	v_exp_f32_e32 v173, v173
	v_exp_f32_e32 v180, v180
	v_exp_f32_e32 v181, v181
	v_rcp_f32_e32 v118, v118
	v_rcp_f32_e32 v119, v119
	v_exp_f32_e32 v178, v178
	v_exp_f32_e32 v179, v179
	v_exp_f32_e32 v174, v174
	v_exp_f32_e32 v175, v175
	v_pk_mul_f32 v[120:121], v[128:129], v[120:121]
	v_pk_mul_f32 v[128:129], v[168:169], v[116:117]
	v_pk_mul_f32 v[116:117], v[170:171], v[114:115]
	v_pk_add_f32 v[180:181], v[180:181], 1.0 op_sel_hi:[1,0]
	v_pk_add_f32 v[172:173], v[172:173], 1.0 op_sel_hi:[1,0]
	v_pk_mul_f32 v[118:119], v[158:159], v[118:119]
	v_pk_add_f32 v[174:175], v[174:175], 1.0 op_sel_hi:[1,0]
	v_cvt_pk_bf16_f32 v114, v118, v119
	v_cvt_pk_bf16_f32 v115, v120, v121
	v_cvt_pk_bf16_f32 v116, v116, v117
	v_cvt_pk_bf16_f32 v117, v128, v129
	v_pk_add_f32 v[178:179], v[178:179], 1.0 op_sel_hi:[1,0]
	v_rcp_f32_e32 v172, v172
	global_store_dwordx4 v[156:157], v[114:117], off
	v_rcp_f32_e32 v173, v173
	v_rcp_f32_e32 v178, v178
	v_rcp_f32_e32 v116, v180
	v_rcp_f32_e32 v117, v181
	v_rcp_f32_e32 v179, v179
	v_rcp_f32_e32 v114, v174
	v_rcp_f32_e32 v115, v175
	v_mul_f32_e32 v118, v165, v165
	v_pk_mul_f32 v[98:99], v[98:99], v[118:119] op_sel_hi:[1,0]
	v_pk_mul_f32 v[100:101], v[100:101], v[118:119] op_sel_hi:[1,0]
	v_pk_mul_f32 v[102:103], v[102:103], v[118:119] op_sel_hi:[1,0]
	v_pk_mul_f32 v[104:105], v[104:105], v[118:119] op_sel_hi:[1,0]
	v_pk_mul_f32 v[106:107], v[100:101], v[116:117]
; __device__ __forceinline__ unsigned cvt_pk_bf16(float lo, float hi) { unsigned r; asm volatile("v_cvt_pk_bf16_f32 %0, %1, %2" : "=v"(r) : "v"(lo), "v"(hi)); return r; }
;     __device__ __forceinline__ void operator()(const f32x4 (&acc)[2][2][4][2], const Unit& u, int wr, int wc, int fr, int fq) const {
;     ...
;         for (int ai = 0; ai < 2; ++ai)
; #pragma unroll
;             for (int m = 0; m < 4; ++m) {
;                 bf16_t* rowp = O + (size_t)(row0 + ai * HALF + m * 16) * ldc + col0;
;                 const float rv = rvv[ai][m], rn = rv * -1.4426950408889634f, r2 = rv * rv;
;                 const f32x4 g0 = acc[ai][0][m][0], g1 = acc[ai][0][m][1], u0 = acc[ai][1][m][0], u1 = acc[ai][1][m][1];
;                 const f32x4 t0 = g0 * rn, t1 = g1 * rn;
;                 f32x4 d0, d1;
; #pragma unroll
;                 for (int k = 0; k < 4; ++k) { d0[k] = __builtin_amdgcn_exp2f(t0[k]); d1[k] = __builtin_amdgcn_exp2f(t1[k]); }
;                 d0 = d0 + 1.0f; d1 = d1 + 1.0f;
; #pragma unroll
;                 for (int k = 0; k < 4; ++k) { d0[k] = __builtin_amdgcn_rcpf(d0[k]); d1[k] = __builtin_amdgcn_rcpf(d1[k]); }
;                 const f32x4 o0 = (g0 * u0) * r2 * d0, o1 = (g1 * u1) * r2 * d1;
;                 u32x4 w;
;                 w.x = cvt_pk_bf16(o0[0], o0[1]); w.y = cvt_pk_bf16(o0[2], o0[3]); w.z = cvt_pk_bf16(o1[0], o1[1]); w.w = cvt_pk_bf16(o1[2], o1[3]);
;                 *(u32x4*)rowp = w;
	v_pk_mul_f32 v[100:101], v[98:99], v[172:173]
	v_pk_mul_f32 v[104:105], v[104:105], v[114:115]
	v_pk_mul_f32 v[102:103], v[102:103], v[178:179]
	v_mul_f32_e32 v108, v191, v191
	v_cvt_pk_bf16_f32 v98, v102, v103
	v_cvt_pk_bf16_f32 v99, v104, v105
	v_cvt_pk_bf16_f32 v100, v100, v101
	v_cvt_pk_bf16_f32 v101, v106, v107
	global_store_dwordx4 v[160:161], v[98:101], off
	v_pk_mul_f32 v[82:83], v[82:83], v[108:109] op_sel_hi:[1,0]
	v_pk_mul_f32 v[84:85], v[84:85], v[108:109] op_sel_hi:[1,0]
	v_mul_f32_e32 v100, 0xbfb8aa3b, v191
	v_pk_mul_f32 v[102:103], v[96:97], v[100:101] op_sel_hi:[1,0]
	v_pk_mul_f32 v[104:105], v[94:95], v[100:101] op_sel_hi:[1,0]
	v_pk_mul_f32 v[106:107], v[92:93], v[100:101] op_sel_hi:[1,0]
	v_pk_mul_f32 v[100:101], v[90:91], v[100:101] op_sel_hi:[1,0]
	v_exp_f32_e32 v106, v106
	v_exp_f32_e32 v100, v100
	v_exp_f32_e32 v101, v101
	v_exp_f32_e32 v107, v107
	v_exp_f32_e32 v104, v104
	v_exp_f32_e32 v105, v105
	v_exp_f32_e32 v102, v102
	v_exp_f32_e32 v103, v103
	v_pk_add_f32 v[106:107], v[106:107], 1.0 op_sel_hi:[1,0]
	v_pk_add_f32 v[100:101], v[100:101], 1.0 op_sel_hi:[1,0]
	v_pk_add_f32 v[104:105], v[104:105], 1.0 op_sel_hi:[1,0]
	v_pk_add_f32 v[102:103], v[102:103], 1.0 op_sel_hi:[1,0]
	v_rcp_f32_e32 v100, v100
	v_rcp_f32_e32 v101, v101
	v_rcp_f32_e32 v106, v106
	v_rcp_f32_e32 v107, v107
	v_rcp_f32_e32 v104, v104
	v_rcp_f32_e32 v105, v105
	v_rcp_f32_e32 v102, v102
	v_rcp_f32_e32 v103, v103
	v_mad_i64_i32 v[98:99], s[20:21], v176, s39, v[148:149]
	v_pk_mul_f32 v[86:87], v[86:87], v[108:109] op_sel_hi:[1,0]
	v_pk_mul_f32 v[88:89], v[88:89], v[108:109] op_sel_hi:[1,0]
	v_pk_mul_f32 v[90:91], v[84:85], v[106:107]
	v_pk_mul_f32 v[84:85], v[82:83], v[100:101]
	v_lshl_add_u64 v[98:99], v[98:99], 0, v[122:123]
	v_pk_mul_f32 v[88:89], v[88:89], v[102:103]
	v_pk_mul_f32 v[86:87], v[86:87], v[104:105]
	v_mul_f32_e32 v92, v192, v192
	v_cvt_pk_bf16_f32 v82, v86, v87
	v_cvt_pk_bf16_f32 v83, v88, v89
	v_cvt_pk_bf16_f32 v84, v84, v85
	v_cvt_pk_bf16_f32 v85, v90, v91
	global_store_dwordx4 v[98:99], v[82:85], off
	v_pk_mul_f32 v[66:67], v[66:67], v[92:93] op_sel_hi:[1,0]
	v_pk_mul_f32 v[68:69], v[68:69], v[92:93] op_sel_hi:[1,0]
	v_mul_f32_e32 v84, 0xbfb8aa3b, v192
	v_pk_mul_f32 v[86:87], v[80:81], v[84:85] op_sel_hi:[1,0]
	v_pk_mul_f32 v[88:89], v[78:79], v[84:85] op_sel_hi:[1,0]
	v_pk_mul_f32 v[90:91], v[76:77], v[84:85] op_sel_hi:[1,0]
	v_pk_mul_f32 v[84:85], v[74:75], v[84:85] op_sel_hi:[1,0]
	v_exp_f32_e32 v90, v90
	v_exp_f32_e32 v84, v84
	v_exp_f32_e32 v85, v85
	v_exp_f32_e32 v91, v91
	v_exp_f32_e32 v88, v88
	v_exp_f32_e32 v89, v89
	v_exp_f32_e32 v86, v86
	v_exp_f32_e32 v87, v87
	v_pk_add_f32 v[90:91], v[90:91], 1.0 op_sel_hi:[1,0]
	v_pk_add_f32 v[84:85], v[84:85], 1.0 op_sel_hi:[1,0]
	v_pk_add_f32 v[88:89], v[88:89], 1.0 op_sel_hi:[1,0]
	v_pk_add_f32 v[86:87], v[86:87], 1.0 op_sel_hi:[1,0]
	v_rcp_f32_e32 v84, v84
	v_rcp_f32_e32 v85, v85
	v_rcp_f32_e32 v90, v90
	v_rcp_f32_e32 v91, v91
	v_rcp_f32_e32 v88, v88
	v_rcp_f32_e32 v89, v89
	v_rcp_f32_e32 v86, v86
	v_rcp_f32_e32 v87, v87
	v_mad_i64_i32 v[82:83], s[20:21], v124, s39, v[148:149]
	v_pk_mul_f32 v[70:71], v[70:71], v[92:93] op_sel_hi:[1,0]
	v_pk_mul_f32 v[72:73], v[72:73], v[92:93] op_sel_hi:[1,0]
	v_pk_mul_f32 v[74:75], v[68:69], v[90:91]
	v_pk_mul_f32 v[68:69], v[66:67], v[84:85]
	v_lshl_add_u64 v[82:83], v[82:83], 0, v[122:123]
	v_pk_mul_f32 v[72:73], v[72:73], v[86:87]
	v_pk_mul_f32 v[70:71], v[70:71], v[88:89]
	v_mul_f32_e32 v76, v177, v177
	v_cvt_pk_bf16_f32 v66, v70, v71
	v_cvt_pk_bf16_f32 v67, v72, v73
	v_cvt_pk_bf16_f32 v68, v68, v69
	v_cvt_pk_bf16_f32 v69, v74, v75
	global_store_dwordx4 v[82:83], v[66:69], off
	v_pk_mul_f32 v[50:51], v[50:51], v[76:77] op_sel_hi:[1,0]
	v_pk_mul_f32 v[52:53], v[52:53], v[76:77] op_sel_hi:[1,0]
	v_mul_f32_e32 v68, 0xbfb8aa3b, v177
	v_pk_mul_f32 v[70:71], v[64:65], v[68:69] op_sel_hi:[1,0]
	v_pk_mul_f32 v[72:73], v[62:63], v[68:69] op_sel_hi:[1,0]
	v_pk_mul_f32 v[74:75], v[60:61], v[68:69] op_sel_hi:[1,0]
	v_pk_mul_f32 v[68:69], v[58:59], v[68:69] op_sel_hi:[1,0]
	v_exp_f32_e32 v74, v74
	v_exp_f32_e32 v68, v68
	v_exp_f32_e32 v69, v69
	v_exp_f32_e32 v75, v75
	v_exp_f32_e32 v72, v72
	v_exp_f32_e32 v73, v73
	v_exp_f32_e32 v70, v70
	v_exp_f32_e32 v71, v71
	v_pk_add_f32 v[74:75], v[74:75], 1.0 op_sel_hi:[1,0]
	v_pk_add_f32 v[68:69], v[68:69], 1.0 op_sel_hi:[1,0]
	v_pk_add_f32 v[72:73], v[72:73], 1.0 op_sel_hi:[1,0]
	v_pk_add_f32 v[70:71], v[70:71], 1.0 op_sel_hi:[1,0]
	v_rcp_f32_e32 v68, v68
	v_rcp_f32_e32 v69, v69
	v_rcp_f32_e32 v74, v74
	v_rcp_f32_e32 v75, v75
	v_rcp_f32_e32 v72, v72
	v_rcp_f32_e32 v73, v73
	v_rcp_f32_e32 v70, v70
	v_rcp_f32_e32 v71, v71
	v_mad_i64_i32 v[66:67], s[20:21], v182, s39, v[148:149]
	v_pk_mul_f32 v[54:55], v[54:55], v[76:77] op_sel_hi:[1,0]
	v_pk_mul_f32 v[56:57], v[56:57], v[76:77] op_sel_hi:[1,0]
	v_pk_mul_f32 v[58:59], v[52:53], v[74:75]
	v_pk_mul_f32 v[52:53], v[50:51], v[68:69]
	v_lshl_add_u64 v[66:67], v[66:67], 0, v[122:123]
	v_pk_mul_f32 v[56:57], v[56:57], v[70:71]
	v_pk_mul_f32 v[54:55], v[54:55], v[72:73]
; __device__ __forceinline__ unsigned cvt_pk_bf16(float lo, float hi) { unsigned r; asm volatile("v_cvt_pk_bf16_f32 %0, %1, %2" : "=v"(r) : "v"(lo), "v"(hi)); return r; }
;     __device__ __forceinline__ void operator()(const f32x4 (&acc)[2][2][4][2], const Unit& u, int wr, int wc, int fr, int fq) const {
;     ...
;         for (int ai = 0; ai < 2; ++ai)
; #pragma unroll
;             for (int m = 0; m < 4; ++m) {
;                 bf16_t* rowp = O + (size_t)(row0 + ai * HALF + m * 16) * ldc + col0;
;                 const float rv = rvv[ai][m], rn = rv * -1.4426950408889634f, r2 = rv * rv;
;                 const f32x4 g0 = acc[ai][0][m][0], g1 = acc[ai][0][m][1], u0 = acc[ai][1][m][0], u1 = acc[ai][1][m][1];
;                 const f32x4 t0 = g0 * rn, t1 = g1 * rn;
;                 f32x4 d0, d1;
; #pragma unroll
;                 for (int k = 0; k < 4; ++k) { d0[k] = __builtin_amdgcn_exp2f(t0[k]); d1[k] = __builtin_amdgcn_exp2f(t1[k]); }
;                 d0 = d0 + 1.0f; d1 = d1 + 1.0f;
; #pragma unroll
;                 for (int k = 0; k < 4; ++k) { d0[k] = __builtin_amdgcn_rcpf(d0[k]); d1[k] = __builtin_amdgcn_rcpf(d1[k]); }
;                 const f32x4 o0 = (g0 * u0) * r2 * d0, o1 = (g1 * u1) * r2 * d1;
;                 u32x4 w;
;                 w.x = cvt_pk_bf16(o0[0], o0[1]); w.y = cvt_pk_bf16(o0[2], o0[3]); w.z = cvt_pk_bf16(o1[0], o1[1]); w.w = cvt_pk_bf16(o1[2], o1[3]);
;                 *(u32x4*)rowp = w;
;             }
	v_mul_f32_e32 v60, v184, v184
	v_cvt_pk_bf16_f32 v50, v54, v55
	v_cvt_pk_bf16_f32 v51, v56, v57
	v_cvt_pk_bf16_f32 v52, v52, v53
	v_cvt_pk_bf16_f32 v53, v58, v59
	global_store_dwordx4 v[66:67], v[50:53], off
	v_pk_mul_f32 v[34:35], v[34:35], v[60:61] op_sel_hi:[1,0]
	v_pk_mul_f32 v[36:37], v[36:37], v[60:61] op_sel_hi:[1,0]
	v_mul_f32_e32 v52, 0xbfb8aa3b, v184
	v_pk_mul_f32 v[54:55], v[48:49], v[52:53] op_sel_hi:[1,0]
	v_pk_mul_f32 v[56:57], v[46:47], v[52:53] op_sel_hi:[1,0]
	v_pk_mul_f32 v[58:59], v[44:45], v[52:53] op_sel_hi:[1,0]
	v_pk_mul_f32 v[52:53], v[42:43], v[52:53] op_sel_hi:[1,0]
	v_exp_f32_e32 v58, v58
	v_exp_f32_e32 v52, v52
	v_exp_f32_e32 v53, v53
	v_exp_f32_e32 v59, v59
	v_exp_f32_e32 v56, v56
	v_exp_f32_e32 v57, v57
	v_exp_f32_e32 v54, v54
	v_exp_f32_e32 v55, v55
	v_pk_add_f32 v[58:59], v[58:59], 1.0 op_sel_hi:[1,0]
	v_pk_add_f32 v[52:53], v[52:53], 1.0 op_sel_hi:[1,0]
	v_pk_add_f32 v[56:57], v[56:57], 1.0 op_sel_hi:[1,0]
	v_pk_add_f32 v[54:55], v[54:55], 1.0 op_sel_hi:[1,0]
	v_rcp_f32_e32 v52, v52
	v_rcp_f32_e32 v53, v53
	v_rcp_f32_e32 v58, v58
	v_rcp_f32_e32 v59, v59
	v_rcp_f32_e32 v56, v56
	v_rcp_f32_e32 v57, v57
	v_rcp_f32_e32 v54, v54
	v_rcp_f32_e32 v55, v55
	v_mad_i64_i32 v[50:51], s[20:21], v183, s39, v[148:149]
	v_pk_mul_f32 v[38:39], v[38:39], v[60:61] op_sel_hi:[1,0]
	v_pk_mul_f32 v[40:41], v[40:41], v[60:61] op_sel_hi:[1,0]
	v_pk_mul_f32 v[42:43], v[36:37], v[58:59]
	v_pk_mul_f32 v[36:37], v[34:35], v[52:53]
	v_lshl_add_u64 v[50:51], v[50:51], 0, v[122:123]
	v_pk_mul_f32 v[40:41], v[40:41], v[54:55]
	v_pk_mul_f32 v[38:39], v[38:39], v[56:57]
	v_mul_f32_e32 v44, v185, v185
	v_cvt_pk_bf16_f32 v34, v38, v39
	v_cvt_pk_bf16_f32 v35, v40, v41
	v_cvt_pk_bf16_f32 v36, v36, v37
	v_cvt_pk_bf16_f32 v37, v42, v43
	global_store_dwordx4 v[50:51], v[34:37], off
	v_pk_mul_f32 v[18:19], v[18:19], v[44:45] op_sel_hi:[1,0]
	v_pk_mul_f32 v[20:21], v[20:21], v[44:45] op_sel_hi:[1,0]
	v_mul_f32_e32 v36, 0xbfb8aa3b, v185
	v_pk_mul_f32 v[38:39], v[32:33], v[36:37] op_sel_hi:[1,0]
	v_pk_mul_f32 v[40:41], v[30:31], v[36:37] op_sel_hi:[1,0]
	v_pk_mul_f32 v[42:43], v[28:29], v[36:37] op_sel_hi:[1,0]
	v_pk_mul_f32 v[36:37], v[26:27], v[36:37] op_sel_hi:[1,0]
	v_exp_f32_e32 v42, v42
	v_exp_f32_e32 v36, v36
	v_exp_f32_e32 v37, v37
	v_exp_f32_e32 v43, v43
	v_exp_f32_e32 v40, v40
	v_exp_f32_e32 v41, v41
	v_exp_f32_e32 v38, v38
	v_exp_f32_e32 v39, v39
	v_pk_add_f32 v[42:43], v[42:43], 1.0 op_sel_hi:[1,0]
	v_pk_add_f32 v[36:37], v[36:37], 1.0 op_sel_hi:[1,0]
	v_pk_add_f32 v[40:41], v[40:41], 1.0 op_sel_hi:[1,0]
	v_pk_add_f32 v[38:39], v[38:39], 1.0 op_sel_hi:[1,0]
	v_rcp_f32_e32 v36, v36
	v_rcp_f32_e32 v37, v37
	v_rcp_f32_e32 v42, v42
	v_rcp_f32_e32 v43, v43
	v_rcp_f32_e32 v40, v40
	v_rcp_f32_e32 v41, v41
	v_rcp_f32_e32 v38, v38
	v_rcp_f32_e32 v39, v39
	v_mad_i64_i32 v[34:35], s[20:21], v127, s39, v[148:149]
	v_pk_mul_f32 v[22:23], v[22:23], v[44:45] op_sel_hi:[1,0]
	v_pk_mul_f32 v[24:25], v[24:25], v[44:45] op_sel_hi:[1,0]
	v_pk_mul_f32 v[26:27], v[20:21], v[42:43]
	v_pk_mul_f32 v[20:21], v[18:19], v[36:37]
	v_lshl_add_u64 v[34:35], v[34:35], 0, v[122:123]
	v_pk_mul_f32 v[24:25], v[24:25], v[38:39]
	v_pk_mul_f32 v[22:23], v[22:23], v[40:41]
	v_mul_f32_e32 v28, v125, v125
	v_cvt_pk_bf16_f32 v18, v22, v23
	v_cvt_pk_bf16_f32 v19, v24, v25
	v_cvt_pk_bf16_f32 v20, v20, v21
	v_cvt_pk_bf16_f32 v21, v26, v27
	global_store_dwordx4 v[34:35], v[18:21], off
	v_pk_mul_f32 v[2:3], v[2:3], v[28:29] op_sel_hi:[1,0]
	v_pk_mul_f32 v[4:5], v[4:5], v[28:29] op_sel_hi:[1,0]
	v_mul_f32_e32 v20, 0xbfb8aa3b, v125
	v_pk_mul_f32 v[22:23], v[16:17], v[20:21] op_sel_hi:[1,0]
	v_pk_mul_f32 v[24:25], v[14:15], v[20:21] op_sel_hi:[1,0]
	v_pk_mul_f32 v[26:27], v[12:13], v[20:21] op_sel_hi:[1,0]
	v_pk_mul_f32 v[20:21], v[10:11], v[20:21] op_sel_hi:[1,0]
	v_exp_f32_e32 v26, v26
	v_exp_f32_e32 v20, v20
	v_exp_f32_e32 v21, v21
	v_exp_f32_e32 v27, v27
	v_exp_f32_e32 v24, v24
	v_exp_f32_e32 v25, v25
	v_exp_f32_e32 v22, v22
	v_exp_f32_e32 v23, v23
	v_pk_add_f32 v[26:27], v[26:27], 1.0 op_sel_hi:[1,0]
	v_pk_add_f32 v[20:21], v[20:21], 1.0 op_sel_hi:[1,0]
	v_pk_add_f32 v[24:25], v[24:25], 1.0 op_sel_hi:[1,0]
	v_pk_add_f32 v[22:23], v[22:23], 1.0 op_sel_hi:[1,0]
	v_rcp_f32_e32 v20, v20
	v_rcp_f32_e32 v21, v21
	v_rcp_f32_e32 v26, v26
	v_rcp_f32_e32 v27, v27
	v_rcp_f32_e32 v24, v24
	v_rcp_f32_e32 v25, v25
	v_rcp_f32_e32 v22, v22
	v_rcp_f32_e32 v23, v23
	v_mad_i64_i32 v[18:19], s[20:21], v126, s39, v[148:149]
	v_lshl_add_u64 v[18:19], v[18:19], 0, v[122:123]
	v_pk_mul_f32 v[6:7], v[6:7], v[28:29] op_sel_hi:[1,0]
	v_pk_mul_f32 v[8:9], v[8:9], v[28:29] op_sel_hi:[1,0]
	v_pk_mul_f32 v[10:11], v[4:5], v[26:27]
	v_pk_mul_f32 v[4:5], v[2:3], v[20:21]
	v_pk_mul_f32 v[8:9], v[8:9], v[22:23]
	v_pk_mul_f32 v[6:7], v[6:7], v[24:25]
	s_nop 0
	v_cvt_pk_bf16_f32 v2, v6, v7
	v_cvt_pk_bf16_f32 v3, v8, v9
	v_cvt_pk_bf16_f32 v4, v4, v5
	v_cvt_pk_bf16_f32 v5, v10, v11
	global_store_dwordx4 v[18:19], v[2:5], off
	s_cbranch_vccnz .LBB0_1555
	s_andn2_b64 vcc, exec, s[0:1]
	s_cbranch_vccnz .LBB0_1554
	s_barrier
	s_branch .LBB0_1554
